# normmod2 -> up counters with the normmod2 H stores sunk to the end of each iteration
# baseline (speedup 1.0000x reference)
.LBB0_205:
	v_mov_b32_e32 v4, v1
	v_cmp_lt_i32_e32 vcc, v196, v195
	v_and_b32_e32 v2, 63, v4
	v_lshlrev_b32_e32 v162, 3, v2
	v_lshl_add_u64 v[2:3], s[14:15], 0, v[12:13]
	v_lshl_add_u64 v[2:3], v[2:3], 0, v[162:163]
	global_load_dwordx2 v[20:21], v[2:3], off sc1
	global_load_dwordx2 v[40:41], v[2:3], off offset:512 sc1
	global_load_dwordx2 v[24:25], v[2:3], off offset:1024 sc1
	global_load_dwordx2 v[42:43], v[2:3], off offset:1536 sc1
	global_load_dwordx2 v[30:31], v[2:3], off offset:2048 sc1
	global_load_dwordx2 v[38:39], v[2:3], off offset:2560 sc1
	global_load_dwordx2 v[22:23], v[2:3], off offset:3072 sc1
	global_load_dwordx2 v[46:47], v[2:3], off offset:3584 sc1
	v_cndmask_b32_e32 v2, v194, v196, vcc
	v_cmp_lt_i32_e32 vcc, v197, v195
	v_lshlrev_b32_e32 v11, 2, v2
	s_mul_i32 s0, s82, 5
	v_cndmask_b32_e32 v2, v194, v197, vcc
	v_cmp_lt_i32_e32 vcc, v198, v195
	s_waitcnt vmcnt(20)
	v_lshlrev_b32_e32 v74, 2, v2
	v_mov_b32_e32 v15, v163
	v_cndmask_b32_e32 v2, v194, v198, vcc
	v_cmp_lt_i32_e32 vcc, v199, v195
	v_lshlrev_b32_e32 v75, 2, v2
	s_waitcnt vmcnt(7)
	v_and_b32_e32 v33, 0xffff0000, v20
	v_cndmask_b32_e32 v2, v194, v199, vcc
	v_cmp_lt_i32_e32 vcc, v200, v195
	v_lshlrev_b32_e32 v76, 2, v2
	s_waitcnt vmcnt(6)
	v_and_b32_e32 v59, 0xffff0000, v40
	v_cndmask_b32_e32 v2, v194, v200, vcc
	v_cmp_lt_i32_e32 vcc, v201, v195
	v_lshlrev_b32_e32 v77, 2, v2
	v_lshlrev_b32_e32 v32, 16, v20
	v_cndmask_b32_e32 v2, v194, v201, vcc
	v_lshlrev_b32_e32 v78, 2, v2
	v_add_u32_e32 v2, 0xfffff000, v10
	v_lshrrev_b32_e32 v2, 10, v2
	v_add_u32_e32 v2, 1, v2
	v_cmp_lt_i32_e32 vcc, s17, v10
	v_lshlrev_b32_e32 v58, 16, v40
	v_mov_b32_e32 v52, v33
	v_cndmask_b32_e32 v2, 0, v2, vcc
	v_add_u32_e32 v5, s0, v2
	v_mov_b64_e32 v[2:3], s[40:41]
	v_mad_i64_i32 v[2:3], s[0:1], v5, s29, v[2:3]
	s_mov_b64 s[0:1], 0x3000
	s_nop 0
	v_lshl_add_u64 v[44:45], v[2:3], 0, s[0:1]
	v_lshl_add_u64 v[60:61], v[2:3], 0, s[36:37]
	v_lshlrev_b32_e32 v2, 4, v4
	v_and_b32_e32 v14, 0x3f0, v2
	v_lshl_add_u64 v[2:3], v[44:45], 0, v[14:15]
	v_lshl_add_u64 v[16:17], v[60:61], 0, v[14:15]
	global_load_dwordx4 v[2:5], v[2:3], off
	v_mov_b32_e32 v53, v59
	global_load_dwordx4 v[16:19], v[16:17], off
	v_lshlrev_b32_e32 v28, 16, v21
	global_load_dwordx4 v[6:9], v14, s[6:7]
	v_lshlrev_b32_e32 v56, 16, v41
	v_mov_b32_e32 v50, v32
	v_mov_b32_e32 v51, v58
	v_pk_mul_f32 v[52:53], v[52:53], v[52:53]
	v_and_b32_e32 v57, 0xffff0000, v41
	v_mov_b32_e32 v40, v28
	v_mov_b32_e32 v41, v56
	v_pk_fma_f32 v[50:51], v[50:51], v[50:51], v[52:53]
	v_and_b32_e32 v29, 0xffff0000, v21
	s_waitcnt vmcnt(6)
	v_and_b32_e32 v35, 0xffff0000, v30
	v_pk_fma_f32 v[40:41], v[40:41], v[40:41], v[50:51]
	s_waitcnt vmcnt(5)
	v_and_b32_e32 v51, 0xffff0000, v38
	v_lshlrev_b32_e32 v34, 16, v30
	v_mov_b32_e32 v48, v29
	v_mov_b32_e32 v49, v57
	v_lshlrev_b32_e32 v50, 16, v38
	v_mov_b32_e32 v54, v35
	v_mov_b32_e32 v55, v51
	v_lshlrev_b32_e32 v26, 16, v31
	v_pk_fma_f32 v[62:63], v[48:49], v[48:49], v[40:41]
	v_lshlrev_b32_e32 v48, 16, v39
	v_mov_b32_e32 v52, v34
	v_mov_b32_e32 v53, v50
	v_pk_mul_f32 v[54:55], v[54:55], v[54:55]
	v_and_b32_e32 v27, 0xffff0000, v31
	v_and_b32_e32 v49, 0xffff0000, v39
	v_mov_b32_e32 v38, v26
	v_mov_b32_e32 v39, v48
	v_pk_fma_f32 v[52:53], v[52:53], v[52:53], v[54:55]
	v_mov_b32_e32 v40, v27
	v_mov_b32_e32 v41, v49
	v_pk_fma_f32 v[38:39], v[38:39], v[38:39], v[52:53]
	v_and_b32_e32 v67, 0xffff0000, v24
	v_and_b32_e32 v71, 0xffff0000, v42
	v_pk_fma_f32 v[68:69], v[40:41], v[40:41], v[38:39]
	v_lshlrev_b32_e32 v66, 16, v24
	v_lshlrev_b32_e32 v70, 16, v42
	v_mov_b32_e32 v80, v67
	v_mov_b32_e32 v81, v71
	v_lshlrev_b32_e32 v64, 16, v25
	s_waitcnt vmcnt(4)
	v_lshlrev_b32_e32 v52, 16, v23
	v_and_b32_e32 v53, 0xffff0000, v23
	v_lshlrev_b32_e32 v54, 16, v22
	v_and_b32_e32 v55, 0xffff0000, v22
	v_mov_b32_e32 v72, v66
	v_mov_b32_e32 v73, v70
	v_pk_mul_f32 v[80:81], v[80:81], v[80:81]
	v_and_b32_e32 v65, 0xffff0000, v25
	v_mov_b32_e32 v42, v64
	v_pk_fma_f32 v[72:73], v[72:73], v[72:73], v[80:81]
	v_mov_b32_e32 v84, v55
	v_mov_b32_e32 v82, v54
	v_mov_b32_e32 v80, v53
	v_add_u32_e32 v10, s16, v10
	s_waitcnt vmcnt(1)
	v_pk_add_f32 v[20:21], v[16:17], 1.0 op_sel_hi:[1,0]
	v_lshl_add_u64 v[16:17], s[18:19], 0, v[12:13]
	v_lshl_add_u64 v[16:17], v[16:17], 0, v[162:163]
	v_or_b32_e32 v162, 0x400, v14
	v_lshl_add_u64 v[36:37], v[44:45], 0, v[162:163]
	v_lshl_add_u64 v[30:31], v[60:61], 0, v[162:163]
	v_or_b32_e32 v162, 0x800, v14
	v_lshl_add_u64 v[40:41], v[44:45], 0, v[162:163]
	v_lshl_add_u64 v[38:39], v[60:61], 0, v[162:163]
	v_or_b32_e32 v162, 0xc00, v14
	v_lshl_add_u64 v[22:23], v[60:61], 0, v[162:163]
	v_lshlrev_b32_e32 v60, 16, v43
	v_and_b32_e32 v61, 0xffff0000, v43
	v_mov_b32_e32 v43, v60
	v_lshl_add_u64 v[24:25], v[44:45], 0, v[162:163]
	v_mov_b32_e32 v44, v65
	v_mov_b32_e32 v45, v61
	v_pk_fma_f32 v[42:43], v[42:43], v[42:43], v[72:73]
	v_pk_add_f32 v[18:19], v[18:19], 1.0 op_sel_hi:[1,0]
	v_pk_fma_f32 v[72:73], v[44:45], v[44:45], v[42:43]
	v_and_b32_e32 v45, 0xffff0000, v46
	v_lshlrev_b32_e32 v44, 16, v46
	v_mov_b32_e32 v85, v45
	v_lshlrev_b32_e32 v42, 16, v47
	v_mov_b32_e32 v83, v44
	v_pk_mul_f32 v[84:85], v[84:85], v[84:85]
	v_and_b32_e32 v43, 0xffff0000, v47
	v_mov_b32_e32 v46, v52
	v_mov_b32_e32 v47, v42
	v_pk_fma_f32 v[82:83], v[82:83], v[82:83], v[84:85]
	v_mov_b32_e32 v81, v43
	v_pk_fma_f32 v[46:47], v[46:47], v[46:47], v[82:83]
	s_add_u32 s18, s18, s24
	v_pk_fma_f32 v[46:47], v[80:81], v[80:81], v[46:47]
	v_mov_b32_e32 v80, v68
	v_mov_b32_e32 v81, v62
	v_mov_b32_e32 v62, v69
	v_pk_add_f32 v[62:63], v[80:81], v[62:63]
	v_mov_b32_e32 v68, v46
	v_mov_b32_e32 v69, v72
	v_pk_add_f32 v[62:63], v[62:63], v[68:69]
	v_mov_b32_e32 v72, v47
	v_pk_add_f32 v[46:47], v[62:63], v[72:73]
	ds_bpermute_b32 v63, v11, v47
	ds_bpermute_b32 v62, v11, v46
	s_addc_u32 s19, s19, s25
	s_add_u32 s14, s14, s24
	s_addc_u32 s15, s15, s25
	s_waitcnt lgkmcnt(0)
	v_pk_add_f32 v[46:47], v[46:47], v[62:63]
	ds_bpermute_b32 v63, v74, v47
	ds_bpermute_b32 v62, v74, v46
	s_waitcnt lgkmcnt(0)
	v_pk_add_f32 v[46:47], v[46:47], v[62:63]
	ds_bpermute_b32 v63, v75, v47
	ds_bpermute_b32 v62, v75, v46
	s_waitcnt lgkmcnt(0)
	v_pk_add_f32 v[46:47], v[46:47], v[62:63]
	ds_bpermute_b32 v63, v76, v47
	ds_bpermute_b32 v62, v76, v46
	s_waitcnt lgkmcnt(0)
	v_pk_add_f32 v[46:47], v[46:47], v[62:63]
	ds_bpermute_b32 v63, v77, v47
	ds_bpermute_b32 v62, v77, v46
	s_waitcnt lgkmcnt(0)
	v_pk_add_f32 v[46:47], v[46:47], v[62:63]
	ds_bpermute_b32 v63, v78, v47
	ds_bpermute_b32 v62, v78, v46
	s_waitcnt lgkmcnt(0)
	v_pk_add_f32 v[46:47], v[46:47], v[62:63]
	s_nop 0
	v_pk_fma_f32 v[62:63], v[46:47], s[30:31], v[164:165] op_sel_hi:[1,0,0]
	s_nop 0
	v_mul_f32_e32 v11, 0x4b800000, v63
	v_cmp_gt_f32_e64 s[38:39], s50, v63
	v_cmp_gt_f32_e32 vcc, s50, v62
	s_nop 0
	v_cndmask_b32_e64 v11, v63, v11, s[38:39]
	v_rsq_f32_e32 v11, v11
	s_nop 0
	v_mul_f32_e32 v15, 0x45800000, v11
	v_cndmask_b32_e64 v68, v11, v15, s[38:39]
	v_mul_f32_e32 v11, 0x4b800000, v62
	v_cndmask_b32_e32 v11, v62, v11, vcc
	v_rsq_f32_e32 v11, v11
	v_pk_mul_f32 v[72:73], v[68:69], v[58:59] op_sel_hi:[0,1]
	v_pk_mul_f32 v[32:33], v[68:69], v[32:33] op_sel_hi:[0,1]
	s_waitcnt vmcnt(0)
	v_pk_mul_f32 v[32:33], v[6:7], v[32:33]
	v_mul_f32_e32 v15, 0x45800000, v11
	v_cndmask_b32_e32 v58, v11, v15, vcc
	v_pk_mul_f32 v[34:35], v[58:59], v[34:35] op_sel_hi:[0,1]
	v_pk_mul_f32 v[6:7], v[6:7], v[34:35]
	v_pk_fma_f32 v[32:33], v[32:33], v[20:21], v[2:3]
	v_pk_mul_f32 v[28:29], v[68:69], v[28:29] op_sel_hi:[0,1]
	v_pk_fma_f32 v[2:3], v[20:21], v[6:7], v[2:3]
	v_pk_mul_f32 v[6:7], v[58:59], v[26:27] op_sel_hi:[0,1]
	v_pk_mul_f32 v[28:29], v[8:9], v[28:29]
	v_pk_mul_f32 v[6:7], v[8:9], v[6:7]
	v_pk_fma_f32 v[28:29], v[28:29], v[18:19], v[4:5]
	v_pk_fma_f32 v[4:5], v[18:19], v[6:7], v[4:5]
	v_cvt_pk_bf16_f32 v32, v32, v33
	v_cvt_pk_bf16_f32 v33, v28, v29
	v_cvt_pk_bf16_f32 v2, v2, v3
	v_cvt_pk_bf16_f32 v3, v4, v5
	v_mov_b32_e32 v100, v32
	v_mov_b32_e32 v101, v33
	v_mov_b32_e32 v102, v2
	v_mov_b32_e32 v103, v3
	global_load_dwordx4 v[2:5], v14, s[6:7] offset:1024
	s_nop 0
	global_load_dwordx4 v[6:9], v[36:37], off
	global_load_dwordx4 v[18:21], v[30:31], off
	v_pk_mul_f32 v[74:75], v[68:69], v[56:57] op_sel_hi:[0,1]
	v_pk_mul_f32 v[26:27], v[58:59], v[50:51] op_sel_hi:[0,1]
	v_pk_mul_f32 v[34:35], v[58:59], v[48:49] op_sel_hi:[0,1]
	v_pk_mul_f32 v[56:57], v[68:69], v[66:67] op_sel_hi:[0,1]
	v_pk_mul_f32 v[46:47], v[68:69], v[64:65] op_sel_hi:[0,1]
	v_pk_mul_f32 v[48:49], v[58:59], v[54:55] op_sel_hi:[0,1]
	v_pk_mul_f32 v[50:51], v[58:59], v[52:53] op_sel_hi:[0,1]
	v_pk_mul_f32 v[32:33], v[68:69], v[70:71] op_sel_hi:[0,1]
	v_pk_mul_f32 v[28:29], v[68:69], v[60:61] op_sel_hi:[0,1]
	v_cmp_lt_i32_e32 vcc, s51, v10
	s_or_b64 s[12:13], vcc, s[12:13]
	s_waitcnt vmcnt(2)
	v_pk_mul_f32 v[30:31], v[72:73], v[2:3]
	v_pk_mul_f32 v[36:37], v[74:75], v[4:5]
	s_waitcnt vmcnt(0)
	v_pk_add_f32 v[18:19], v[18:19], 1.0 op_sel_hi:[1,0]
	v_pk_add_f32 v[20:21], v[20:21], 1.0 op_sel_hi:[1,0]
	v_pk_mul_f32 v[2:3], v[2:3], v[26:27]
	v_pk_mul_f32 v[4:5], v[4:5], v[34:35]
	v_pk_fma_f32 v[30:31], v[30:31], v[18:19], v[6:7]
	v_pk_fma_f32 v[36:37], v[36:37], v[20:21], v[8:9]
	v_pk_fma_f32 v[2:3], v[18:19], v[2:3], v[6:7]
	v_pk_fma_f32 v[4:5], v[20:21], v[4:5], v[8:9]
	v_cvt_pk_bf16_f32 v30, v30, v31
	v_cvt_pk_bf16_f32 v31, v36, v37
	v_cvt_pk_bf16_f32 v2, v2, v3
	v_cvt_pk_bf16_f32 v3, v4, v5
	v_mov_b32_e32 v104, v30
	v_mov_b32_e32 v105, v31
	v_mov_b32_e32 v106, v2
	v_mov_b32_e32 v107, v3
	global_load_dwordx4 v[2:5], v14, s[6:7] offset:2048
	s_nop 0
	global_load_dwordx4 v[6:9], v[40:41], off
	global_load_dwordx4 v[18:21], v[38:39], off
	s_waitcnt vmcnt(2)
	v_pk_mul_f32 v[26:27], v[56:57], v[2:3]
	v_pk_mul_f32 v[30:31], v[46:47], v[4:5]
	s_waitcnt vmcnt(0)
	v_pk_add_f32 v[18:19], v[18:19], 1.0 op_sel_hi:[1,0]
	v_pk_add_f32 v[20:21], v[20:21], 1.0 op_sel_hi:[1,0]
	v_pk_mul_f32 v[2:3], v[48:49], v[2:3]
	v_pk_mul_f32 v[4:5], v[50:51], v[4:5]
	v_pk_fma_f32 v[26:27], v[26:27], v[18:19], v[6:7]
	v_pk_fma_f32 v[30:31], v[30:31], v[20:21], v[8:9]
	v_pk_fma_f32 v[2:3], v[2:3], v[18:19], v[6:7]
	v_pk_fma_f32 v[4:5], v[4:5], v[20:21], v[8:9]
	v_cvt_pk_bf16_f32 v26, v26, v27
	v_cvt_pk_bf16_f32 v27, v30, v31
	v_cvt_pk_bf16_f32 v2, v2, v3
	v_cvt_pk_bf16_f32 v3, v4, v5
	v_mov_b32_e32 v108, v26
	v_mov_b32_e32 v109, v27
	v_mov_b32_e32 v110, v2
	v_mov_b32_e32 v111, v3
	global_load_dwordx4 v[2:5], v14, s[6:7] offset:3072
	s_nop 0
	global_load_dwordx4 v[6:9], v[24:25], off
	global_load_dwordx4 v[18:21], v[22:23], off
	s_waitcnt vmcnt(2)
	v_pk_mul_f32 v[14:15], v[32:33], v[2:3]
	v_pk_mul_f32 v[22:23], v[28:29], v[4:5]
	s_waitcnt vmcnt(0)
	v_pk_add_f32 v[18:19], v[18:19], 1.0 op_sel_hi:[1,0]
	v_pk_add_f32 v[20:21], v[20:21], 1.0 op_sel_hi:[1,0]
	v_pk_fma_f32 v[14:15], v[14:15], v[18:19], v[6:7]
	v_pk_fma_f32 v[22:23], v[22:23], v[20:21], v[8:9]
	v_cvt_pk_bf16_f32 v14, v14, v15
	v_cvt_pk_bf16_f32 v15, v22, v23
	v_mov_b32_e32 v112, v14
	v_mov_b32_e32 v113, v15
	v_pk_mul_f32 v[14:15], v[58:59], v[44:45] op_sel_hi:[0,1]
	v_pk_mul_f32 v[2:3], v[14:15], v[2:3]
	s_nop 0
	v_pk_fma_f32 v[2:3], v[2:3], v[18:19], v[6:7]
	v_pk_mul_f32 v[6:7], v[58:59], v[42:43] op_sel_hi:[0,1]
	v_pk_mul_f32 v[4:5], v[6:7], v[4:5]
	v_cvt_pk_bf16_f32 v2, v2, v3
	v_pk_fma_f32 v[4:5], v[4:5], v[20:21], v[8:9]
	s_nop 0
	v_cvt_pk_bf16_f32 v3, v4, v5
	global_store_dwordx2 v[16:17], v[100:101], off sc1
	global_store_dwordx2 v[16:17], v[102:103], off offset:2048 sc1
	global_store_dwordx2 v[16:17], v[104:105], off offset:512 sc1
	global_store_dwordx2 v[16:17], v[106:107], off offset:2560 sc1
	global_store_dwordx2 v[16:17], v[108:109], off offset:1024 sc1
	global_store_dwordx2 v[16:17], v[110:111], off offset:3072 sc1
	global_store_dwordx2 v[16:17], v[112:113], off offset:1536 sc1
	global_store_dwordx2 v[16:17], v[2:3], off offset:3584 sc1
	s_andn2_b64 exec, exec, s[12:13]
	s_cbranch_execnz .LBB0_205
